# P0 weight prep: the eight small matrices dealt to rotated virtual-block ranges (max 5 tile-steps per block instead of 12 in layer 1, 10 instead of 17 in layer 0)
# speedup vs baseline: 1.0070x; 1.0070x over previous
.LBB0_66:
	v_readlane_b32 s0, v254, 51
	s_sub_i32 s56, s12, 0x100
	s_and_b32 s56, s56, 0x1ff
	s_cmpk_lt_i32 s56, 0x80
	s_mul_i32 s88, s0, 0x180000
	v_readlane_b32 s40, v251, 22
	s_cselect_b64 s[6:7], -1, 0
	s_lshl_b64 s[0:1], s[88:89], 2
	v_readlane_b32 s54, v251, 36
	v_readlane_b32 s55, v251, 37
	s_add_u32 s0, s54, s0
	s_addc_u32 s1, s55, s1
	v_mov_b32_e32 v0, v194
	s_and_b64 vcc, exec, s[6:7]
	v_readlane_b32 s41, v251, 23
	v_readlane_b32 s42, v251, 24
	v_readlane_b32 s43, v251, 25
	v_readlane_b32 s44, v251, 26
	v_readlane_b32 s45, v251, 27
	v_readlane_b32 s46, v251, 28
	v_readlane_b32 s47, v251, 29
	v_readlane_b32 s48, v251, 30
	v_readlane_b32 s49, v251, 31
	v_readlane_b32 s50, v251, 32
	v_readlane_b32 s51, v251, 33
	v_readlane_b32 s52, v251, 34
	v_readlane_b32 s53, v251, 35
	s_cbranch_vccz .LBB0_73
	v_lshlrev_b32_e32 v2, 2, v0
	v_and_b32_e32 v21, 60, v2
	v_lshlrev_b32_e32 v2, 4, v0
	v_and_b32_e32 v2, 48, v2
	v_bfe_u32 v20, v0, 4, 4
	v_mul_u32_u24_e32 v5, 0x41, v2
	v_lshl_add_u32 v3, v21, 2, s13
	v_bfe_u32 v22, v0, 2, 6
	v_mul_u32_u24_e32 v4, 0x104, v20
	v_lshlrev_b32_e32 v5, 2, v5
	v_and_b32_e32 v0, 0xfc, v0
	v_add3_u32 v23, s13, v5, v0
	v_add3_u32 v24, s13, v0, v5
	s_lshl_b32 s2, s56, 6
	s_lshl_b32 s10, s82, 6
	v_add_u32_e32 v25, v3, v4
	v_lshlrev_b32_e32 v0, 1, v2
	s_mov_b32 s11, s56
	s_branch .LBB0_69

.LBB0_73:
	v_cndmask_b32_e64 v2, 0, 1, s[6:7]
	v_mov_b32_e32 v0, v194
	v_cmp_ne_u32_e64 s[4:5], 1, v2
	s_sub_i32 s56, s12, 0x180
	s_and_b32 s56, s56, 0x1ff
	s_cmpk_lt_i32 s56, 0x80
	s_cbranch_scc0 .LBB0_80
	v_lshlrev_b32_e32 v2, 2, v0
	v_and_b32_e32 v21, 60, v2
	v_lshlrev_b32_e32 v2, 4, v0
	v_and_b32_e32 v2, 48, v2
	v_bfe_u32 v20, v0, 4, 4
	v_mul_u32_u24_e32 v5, 0x41, v2
	s_add_u32 s6, s0, 0x200000
	v_lshl_add_u32 v3, v21, 2, s13
	v_bfe_u32 v22, v0, 2, 6
	v_mul_u32_u24_e32 v4, 0x104, v20
	v_lshlrev_b32_e32 v5, 2, v5
	v_and_b32_e32 v0, 0xfc, v0
	s_addc_u32 s7, s1, 0
	v_add3_u32 v23, s13, v5, v0
	v_add3_u32 v24, s13, v0, v5
	s_lshl_b32 s2, s56, 6
	s_lshl_b32 s14, s82, 6
	v_add_u32_e32 v25, v3, v4
	v_lshlrev_b32_e32 v0, 1, v2
	s_mov_b32 s15, s56
	s_branch .LBB0_76

.LBB0_80:
	v_mov_b32_e32 v0, v194
	s_sub_i32 s56, s12, 0x100
	s_and_b32 s56, s56, 0x1ff
	s_cmpk_lt_i32 s56, 0x80
	s_cbranch_scc0 .LBB0_87
	v_lshlrev_b32_e32 v2, 2, v0
	v_and_b32_e32 v21, 60, v2
	v_lshlrev_b32_e32 v2, 4, v0
	v_and_b32_e32 v2, 48, v2
	v_bfe_u32 v20, v0, 4, 4
	v_mul_u32_u24_e32 v5, 0x41, v2
	s_add_u32 s0, s0, 0x400000
	v_lshl_add_u32 v3, v21, 2, s13
	v_bfe_u32 v22, v0, 2, 6
	v_mul_u32_u24_e32 v4, 0x104, v20
	v_lshlrev_b32_e32 v5, 2, v5
	v_and_b32_e32 v0, 0xfc, v0
	s_addc_u32 s1, s1, 0
	v_add3_u32 v23, s13, v5, v0
	v_add3_u32 v24, s13, v0, v5
	s_lshl_b32 s2, s56, 6
	s_lshl_b32 s8, s82, 6
	v_add_u32_e32 v25, v3, v4
	v_lshlrev_b32_e32 v0, 1, v2
	s_mov_b32 s9, s56
	s_branch .LBB0_83

.LBB0_94:
	v_readlane_b32 s0, v254, 51
	s_lshl_b32 s14, s0, 1
	s_sub_i32 s56, s12, 0x180
	s_and_b32 s56, s56, 0x1ff
	s_cmp_lt_i32 s56, 64
	s_cselect_b64 s[0:1], -1, 0
	s_mov_b32 s15, s89
	v_mov_b32_e32 v0, v194
	s_and_b64 vcc, exec, s[0:1]
	s_cbranch_vccz .LBB0_101
	v_lshlrev_b32_e32 v2, 2, v0
	v_and_b32_e32 v21, 60, v2
	v_lshlrev_b32_e32 v2, 4, v0
	v_readlane_b32 s40, v251, 22
	v_and_b32_e32 v2, 48, v2
	s_lshl_b64 s[4:5], s[14:15], 20
	v_readlane_b32 s50, v251, 32
	v_bfe_u32 v20, v0, 4, 4
	v_mul_u32_u24_e32 v5, 0x41, v2
	v_readlane_b32 s51, v251, 33
	s_add_u32 s4, s50, s4
	v_lshl_add_u32 v3, v21, 2, s13
	v_bfe_u32 v22, v0, 2, 6
	v_mul_u32_u24_e32 v4, 0x104, v20
	v_lshlrev_b32_e32 v5, 2, v5
	v_and_b32_e32 v0, 0xfc, v0
	s_addc_u32 s5, s51, s5
	v_add3_u32 v23, s13, v5, v0
	v_add3_u32 v24, s13, v0, v5
	s_lshl_b32 s2, s56, 6
	s_lshl_b32 s10, s82, 6
	v_add_u32_e32 v25, v3, v4
	v_lshlrev_b32_e32 v0, 1, v2
	s_mov_b32 s11, s56
	v_readlane_b32 s41, v251, 23
	v_readlane_b32 s42, v251, 24
	v_readlane_b32 s43, v251, 25
	v_readlane_b32 s44, v251, 26
	v_readlane_b32 s45, v251, 27
	v_readlane_b32 s46, v251, 28
	v_readlane_b32 s47, v251, 29
	v_readlane_b32 s48, v251, 30
	v_readlane_b32 s49, v251, 31
	v_readlane_b32 s52, v251, 34
	v_readlane_b32 s53, v251, 35
	v_readlane_b32 s54, v251, 36
	v_readlane_b32 s55, v251, 37
	s_branch .LBB0_97

.LBB0_101:
	s_sub_i32 s56, s12, 0x1d0
	s_and_b32 s56, s56, 0x1ff
	s_cmp_lt_i32 s56, 2
	s_cselect_b64 s[4:5], -1, 0
	s_cmp_gt_i32 s56, 1
	v_mov_b32_e32 v0, v194
	s_cbranch_scc1 .LBB0_108
	v_lshlrev_b32_e32 v2, 2, v0
	v_and_b32_e32 v21, 60, v2
	v_lshlrev_b32_e32 v2, 4, v0
	v_readlane_b32 s40, v251, 22
	v_and_b32_e32 v2, 48, v2
	s_lshl_b64 s[6:7], s[14:15], 15
	v_readlane_b32 s52, v251, 34
	v_bfe_u32 v20, v0, 4, 4
	v_mul_u32_u24_e32 v5, 0x41, v2
	v_readlane_b32 s53, v251, 35
	s_add_u32 s6, s52, s6
	v_lshl_add_u32 v3, v21, 2, s13
	v_bfe_u32 v22, v0, 2, 6
	v_mul_u32_u24_e32 v4, 0x104, v20
	v_lshlrev_b32_e32 v5, 2, v5
	v_and_b32_e32 v0, 0xfc, v0
	s_addc_u32 s7, s53, s7
	v_add3_u32 v23, s13, v5, v0
	v_add3_u32 v24, s13, v0, v5
	s_lshl_b32 s2, s56, 6
	s_lshl_b32 s15, s82, 6
	v_add_u32_e32 v25, v3, v4
	v_lshlrev_b32_e32 v0, 1, v2
	s_mov_b32 s20, s56
	v_readlane_b32 s41, v251, 23
	v_readlane_b32 s42, v251, 24
	v_readlane_b32 s43, v251, 25
	v_readlane_b32 s44, v251, 26
	v_readlane_b32 s45, v251, 27
	v_readlane_b32 s46, v251, 28
	v_readlane_b32 s47, v251, 29
	v_readlane_b32 s48, v251, 30
	v_readlane_b32 s49, v251, 31
	v_readlane_b32 s50, v251, 32
	v_readlane_b32 s51, v251, 33
	v_readlane_b32 s54, v251, 36
	v_readlane_b32 s55, v251, 37
	s_branch .LBB0_104

.LBB0_108:
	s_or_b32 s6, s14, 1
	s_mov_b32 s7, s89
	v_writelane_b32 v255, s6, 3
	v_mov_b32_e32 v0, v194
	s_nop 0
	v_writelane_b32 v255, s7, 4
	s_sub_i32 s56, s12, 0x1c0
	s_and_b32 s56, s56, 0x1ff
	s_cmp_lt_i32 s56, 64
	s_cbranch_scc0 .LBB0_115
	v_lshlrev_b32_e32 v2, 2, v0
	v_readlane_b32 s0, v255, 3
	v_and_b32_e32 v21, 60, v2
	v_lshlrev_b32_e32 v2, 4, v0
	v_readlane_b32 s1, v255, 4
	v_readlane_b32 s40, v251, 22
	v_and_b32_e32 v2, 48, v2
	s_lshl_b64 s[0:1], s[0:1], 20
	v_readlane_b32 s50, v251, 32
	v_bfe_u32 v20, v0, 4, 4
	v_mul_u32_u24_e32 v5, 0x41, v2
	v_readlane_b32 s51, v251, 33
	s_add_u32 s0, s50, s0
	v_lshl_add_u32 v3, v21, 2, s13
	v_bfe_u32 v22, v0, 2, 6
	v_mul_u32_u24_e32 v4, 0x104, v20
	v_lshlrev_b32_e32 v5, 2, v5
	v_and_b32_e32 v0, 0xfc, v0
	v_readlane_b32 s38, v253, 23
	s_addc_u32 s1, s51, s1
	v_add3_u32 v23, s13, v5, v0
	v_add3_u32 v24, s13, v0, v5
	s_lshl_b32 s2, s56, 6
	s_lshl_b32 s10, s82, 6
	v_add_u32_e32 v25, v3, v4
	v_lshlrev_b32_e32 v0, 1, v2
	s_mov_b32 s11, s56
	v_readlane_b32 s39, v253, 24
	v_readlane_b32 s41, v251, 23
	v_readlane_b32 s42, v251, 24
	v_readlane_b32 s43, v251, 25
	v_readlane_b32 s44, v251, 26
	v_readlane_b32 s45, v251, 27
	v_readlane_b32 s46, v251, 28
	v_readlane_b32 s47, v251, 29
	v_readlane_b32 s48, v251, 30
	v_readlane_b32 s49, v251, 31
	v_readlane_b32 s52, v251, 34
	v_readlane_b32 s53, v251, 35
	v_readlane_b32 s54, v251, 36
	v_readlane_b32 s55, v251, 37
	s_branch .LBB0_111

.LBB0_115:
	v_mov_b32_e32 v0, v194
	s_sub_i32 s56, s12, 0x1d2
	s_and_b32 s56, s56, 0x1ff
	s_cmp_lt_i32 s56, 2
	s_cbranch_scc0 .LBB0_122
	v_lshlrev_b32_e32 v2, 2, v0
	v_readlane_b32 s0, v255, 3
	v_and_b32_e32 v21, 60, v2
	v_lshlrev_b32_e32 v2, 4, v0
	v_readlane_b32 s1, v255, 4
	v_readlane_b32 s40, v251, 22
	v_and_b32_e32 v2, 48, v2
	s_lshl_b64 s[0:1], s[0:1], 15
	v_readlane_b32 s52, v251, 34
	v_bfe_u32 v20, v0, 4, 4
	v_mul_u32_u24_e32 v5, 0x41, v2
	v_readlane_b32 s53, v251, 35
	s_add_u32 s0, s52, s0
	v_lshl_add_u32 v3, v21, 2, s13
	v_bfe_u32 v22, v0, 2, 6
	v_mul_u32_u24_e32 v4, 0x104, v20
	v_lshlrev_b32_e32 v5, 2, v5
	v_and_b32_e32 v0, 0xfc, v0
	v_readlane_b32 s20, v253, 25
	s_addc_u32 s1, s53, s1
	v_add3_u32 v23, s13, v5, v0
	v_add3_u32 v24, s13, v0, v5
	s_mov_b32 s12, s56
	s_lshl_b32 s2, s56, 6
	s_lshl_b32 s8, s82, 6
	v_add_u32_e32 v25, v3, v4
	v_lshlrev_b32_e32 v0, 1, v2
	v_readlane_b32 s21, v253, 26
	v_readlane_b32 s41, v251, 23
	v_readlane_b32 s42, v251, 24
	v_readlane_b32 s43, v251, 25
	v_readlane_b32 s44, v251, 26
	v_readlane_b32 s45, v251, 27
	v_readlane_b32 s46, v251, 28
	v_readlane_b32 s47, v251, 29
	v_readlane_b32 s48, v251, 30
	v_readlane_b32 s49, v251, 31
	v_readlane_b32 s50, v251, 32
	v_readlane_b32 s51, v251, 33
	v_readlane_b32 s54, v251, 36
	v_readlane_b32 s55, v251, 37
	s_branch .LBB0_118
